# GDN pre-stage decay-mask epilogue: 32 per-element gate reads from LDS hoisted and waited in three batches instead of 32 read-wait pairs (on stack r40)
# speedup vs baseline: 1.0057x; 1.0057x over previous
.LBB0_327:
	ds_read_b128 v[150:153], v59
	ds_read_b128 v[154:157], v148
	s_add_i32 s38, s38, 32
	s_cmp_gt_u32 s38, 55
	s_waitcnt lgkmcnt(0)
	v_mfma_f32_32x32x2_f32 v[2:17], v150, v154, v[2:17]
	v_mfma_f32_32x32x2_f32 v[2:17], v151, v155, v[2:17]
	v_mfma_f32_32x32x2_f32 v[2:17], v152, v156, v[2:17]
	v_mfma_f32_32x32x2_f32 v[2:17], v153, v157, v[2:17]
	ds_read_b128 v[150:153], v59 offset:32
	ds_read_b128 v[154:157], v148 offset:32
	s_waitcnt lgkmcnt(0)
	v_mfma_f32_32x32x2_f32 v[2:17], v150, v154, v[2:17]
	v_mfma_f32_32x32x2_f32 v[2:17], v151, v155, v[2:17]
	v_mfma_f32_32x32x2_f32 v[2:17], v152, v156, v[2:17]
	v_mfma_f32_32x32x2_f32 v[2:17], v153, v157, v[2:17]
	ds_read_b128 v[150:153], v59 offset:64
	ds_read_b128 v[154:157], v148 offset:64
	s_waitcnt lgkmcnt(0)
	v_mfma_f32_32x32x2_f32 v[2:17], v150, v154, v[2:17]
	v_mfma_f32_32x32x2_f32 v[2:17], v151, v155, v[2:17]
	v_mfma_f32_32x32x2_f32 v[2:17], v152, v156, v[2:17]
	v_mfma_f32_32x32x2_f32 v[2:17], v153, v157, v[2:17]
	ds_read_b128 v[150:153], v59 offset:96
	ds_read_b128 v[154:157], v148 offset:96
	v_add_u32_e32 v148, 0x80, v148
	v_add_u32_e32 v59, 0x80, v59
	s_waitcnt lgkmcnt(0)
	v_mfma_f32_32x32x2_f32 v[2:17], v150, v154, v[2:17]
	v_mfma_f32_32x32x2_f32 v[2:17], v151, v155, v[2:17]
	v_mfma_f32_32x32x2_f32 v[2:17], v152, v156, v[2:17]
	v_mfma_f32_32x32x2_f32 v[2:17], v153, v157, v[2:17]
	s_cbranch_scc0 .LBB0_327
	ds_read_b32 v59, v70
	ds_read_b32 v197, v85
	ds_read_b32 v198, v86
	ds_read_b32 v199, v87
	ds_read_b32 v200, v88
	ds_read_b32 v201, v89
	ds_read_b32 v202, v90
	ds_read_b32 v203, v91
	ds_read_b32 v204, v108
	ds_read_b32 v205, v109
	ds_read_b32 v206, v110
	ds_read_b32 v207, v111
	ds_read_b32 v208, v112
	s_waitcnt lgkmcnt(0)
	ds_read_b32 v209, v113
	ds_read_b32 v210, v114
	ds_read_b32 v211, v115
	ds_read_b32 v212, v116
	ds_read_b32 v213, v117
	ds_read_b32 v214, v118
	ds_read_b32 v215, v119
	ds_read_b32 v216, v120
	ds_read_b32 v217, v121
	ds_read_b32 v218, v122
	ds_read_b32 v219, v123
	ds_read_b32 v220, v124
	s_waitcnt lgkmcnt(0)
	ds_read_b32 v221, v125
	ds_read_b32 v222, v126
	ds_read_b32 v223, v127
	ds_read_b32 v224, v128
	ds_read_b32 v225, v129
	ds_read_b32 v226, v130
	ds_read_b32 v227, v131
	ds_read_b32 v228, v132
	s_waitcnt lgkmcnt(0)
	v_mov_b32_e32 v148, 0
	s_and_saveexec_b64 s[38:39], s[34:35]
	s_cbranch_execz .LBB0_330
	v_mov_b32_e32 v148, v197
	v_sub_f32_e32 v148, v148, v59
	v_mul_f32_e32 v148, 0x3fb8aa3b, v148
	v_exp_f32_e32 v148, v148

.LBB0_333:
	v_readlane_b32 s40, v254, 29
	v_mov_b32_e32 v149, 0
	v_readlane_b32 s41, v254, 30
	s_and_saveexec_b64 s[44:45], s[40:41]
	s_cbranch_execz .LBB0_335
	v_mov_b32_e32 v149, v198
	v_mul_f32_e32 v2, v2, v149
	v_mul_f32_e32 v149, v148, v2

.LBB0_336:
	s_or_b64 exec, exec, s[38:39]
	v_readlane_b32 s40, v254, 31
	s_nop 4
	v_mov_b32_e32 v2, 0
	v_readlane_b32 s41, v254, 32
	ds_write_b32 v147, v149
	s_and_saveexec_b64 s[38:39], s[40:41]
	s_cbranch_execz .LBB0_338
	v_mov_b32_e32 v2, v199
	v_sub_f32_e32 v2, v2, v59
	v_mul_f32_e32 v2, 0x3fb8aa3b, v2
	v_exp_f32_e32 v2, v2

.LBB0_341:
	v_mov_b32_e32 v148, 0
	s_and_saveexec_b64 s[44:45], s[34:35]
	s_cbranch_execz .LBB0_343
	v_mov_b32_e32 v148, v200
	v_mul_f32_e32 v3, v3, v148
	v_mul_f32_e32 v148, v2, v3

.LBB0_344:
	s_or_b64 exec, exec, s[38:39]
	v_readlane_b32 s40, v254, 33
	v_mov_b32_e32 v2, 0
	v_readlane_b32 s41, v254, 34
	ds_write_b32 v147, v148 offset:272
	s_and_saveexec_b64 s[38:39], s[40:41]
	s_cbranch_execz .LBB0_346
	v_mov_b32_e32 v2, v201
	v_sub_f32_e32 v2, v2, v59
	v_mul_f32_e32 v2, 0x3fb8aa3b, v2
	v_exp_f32_e32 v2, v2

.LBB0_349:
	v_readlane_b32 s40, v254, 35
	v_mov_b32_e32 v3, 0
	v_readlane_b32 s41, v254, 36
	s_and_saveexec_b64 s[44:45], s[40:41]
	s_cbranch_execz .LBB0_351
	v_mov_b32_e32 v3, v202
	v_mul_f32_e32 v3, v4, v3
	v_mul_f32_e32 v3, v2, v3

.LBB0_352:
	s_or_b64 exec, exec, s[38:39]
	v_readlane_b32 s40, v254, 37
	v_mov_b32_e32 v2, 0
	v_readlane_b32 s41, v254, 38
	ds_write_b32 v147, v3 offset:544
	s_and_saveexec_b64 s[38:39], s[40:41]
	s_cbranch_execz .LBB0_354
	v_mov_b32_e32 v2, v203
	v_sub_f32_e32 v2, v2, v59
	v_mul_f32_e32 v2, 0x3fb8aa3b, v2
	v_exp_f32_e32 v2, v2

.LBB0_357:
	v_readlane_b32 s40, v254, 39
	v_mov_b32_e32 v3, 0
	v_readlane_b32 s41, v254, 40
	s_and_saveexec_b64 s[44:45], s[40:41]
	s_cbranch_execz .LBB0_359
	v_mov_b32_e32 v3, v204
	v_mul_f32_e32 v3, v5, v3
	v_mul_f32_e32 v3, v2, v3

.LBB0_360:
	s_or_b64 exec, exec, s[38:39]
	v_mov_b32_e32 v2, 0
	ds_write_b32 v147, v3 offset:816
	s_and_saveexec_b64 s[38:39], s[36:37]
	s_cbranch_execz .LBB0_362
	v_mov_b32_e32 v2, v205
	v_sub_f32_e32 v2, v2, v59
	v_mul_f32_e32 v2, 0x3fb8aa3b, v2
	v_exp_f32_e32 v2, v2

.LBB0_365:
	v_readlane_b32 s40, v254, 41
	v_mov_b32_e32 v3, 0
	v_readlane_b32 s41, v254, 42
	s_and_saveexec_b64 s[44:45], s[40:41]
	s_cbranch_execz .LBB0_367
	v_mov_b32_e32 v3, v206
	v_mul_f32_e32 v3, v6, v3
	v_mul_f32_e32 v3, v2, v3

.LBB0_368:
	s_or_b64 exec, exec, s[38:39]
	v_readlane_b32 s40, v254, 43
	v_mov_b32_e32 v2, 0
	v_readlane_b32 s41, v254, 44
	ds_write_b32 v147, v3 offset:2176
	s_and_saveexec_b64 s[38:39], s[40:41]
	s_cbranch_execz .LBB0_370
	v_mov_b32_e32 v2, v207
	v_sub_f32_e32 v2, v2, v59
	v_mul_f32_e32 v2, 0x3fb8aa3b, v2
	v_exp_f32_e32 v2, v2

.LBB0_373:
	v_readlane_b32 s40, v254, 45
	v_mov_b32_e32 v3, 0
	v_readlane_b32 s41, v254, 46
	s_and_saveexec_b64 s[44:45], s[40:41]
	s_cbranch_execz .LBB0_375
	v_mov_b32_e32 v3, v208
	v_mul_f32_e32 v3, v7, v3
	v_mul_f32_e32 v3, v2, v3

.LBB0_376:
	s_or_b64 exec, exec, s[38:39]
	v_readlane_b32 s40, v254, 47
	v_mov_b32_e32 v2, 0
	v_readlane_b32 s41, v254, 48
	ds_write_b32 v147, v3 offset:2448
	s_and_saveexec_b64 s[38:39], s[40:41]
	s_cbranch_execz .LBB0_378
	v_mov_b32_e32 v2, v209
	v_sub_f32_e32 v2, v2, v59
	v_mul_f32_e32 v2, 0x3fb8aa3b, v2
	v_exp_f32_e32 v2, v2

.LBB0_381:
	v_readlane_b32 s40, v254, 49
	v_mov_b32_e32 v3, 0
	v_readlane_b32 s41, v254, 50
	s_and_saveexec_b64 s[44:45], s[40:41]
	s_cbranch_execz .LBB0_383
	v_mov_b32_e32 v3, v210
	v_mul_f32_e32 v3, v8, v3
	v_mul_f32_e32 v3, v2, v3

.LBB0_384:
	s_or_b64 exec, exec, s[38:39]
	v_readlane_b32 s40, v254, 51
	v_mov_b32_e32 v2, 0
	v_readlane_b32 s41, v254, 52
	ds_write_b32 v147, v3 offset:2720
	s_and_saveexec_b64 s[38:39], s[40:41]
	s_cbranch_execz .LBB0_386
	v_mov_b32_e32 v2, v211
	v_sub_f32_e32 v2, v2, v59
	v_mul_f32_e32 v2, 0x3fb8aa3b, v2
	v_exp_f32_e32 v2, v2

.LBB0_389:
	v_readlane_b32 s40, v254, 53
	v_mov_b32_e32 v3, 0
	v_readlane_b32 s41, v254, 54
	s_and_saveexec_b64 s[44:45], s[40:41]
	s_cbranch_execz .LBB0_391
	v_mov_b32_e32 v3, v212
	v_mul_f32_e32 v3, v9, v3
	v_mul_f32_e32 v3, v2, v3

.LBB0_392:
	s_or_b64 exec, exec, s[38:39]
	v_mov_b32_e32 v2, 0
	ds_write_b32 v147, v3 offset:2992
	s_and_saveexec_b64 s[38:39], s[70:71]
	s_cbranch_execz .LBB0_394
	v_mov_b32_e32 v2, v213
	v_sub_f32_e32 v2, v2, v59
	v_mul_f32_e32 v2, 0x3fb8aa3b, v2
	v_exp_f32_e32 v2, v2

.LBB0_397:
	v_readlane_b32 s40, v254, 55
	v_mov_b32_e32 v3, 0
	v_readlane_b32 s41, v254, 56
	s_and_saveexec_b64 s[44:45], s[40:41]
	s_cbranch_execz .LBB0_399
	v_mov_b32_e32 v3, v214
	v_mul_f32_e32 v3, v10, v3
	v_mul_f32_e32 v3, v2, v3

.LBB0_400:
	s_or_b64 exec, exec, s[38:39]
	v_mov_b32_e32 v2, 0
	ds_write_b32 v147, v3 offset:4352
	s_and_saveexec_b64 s[38:39], s[68:69]
	s_cbranch_execz .LBB0_402
	v_mov_b32_e32 v2, v215
	v_sub_f32_e32 v2, v2, v59
	v_mul_f32_e32 v2, 0x3fb8aa3b, v2
	v_exp_f32_e32 v2, v2

.LBB0_405:
	v_readlane_b32 s40, v254, 57
	v_mov_b32_e32 v3, 0
	v_readlane_b32 s41, v254, 58
	s_and_saveexec_b64 s[44:45], s[40:41]
	s_cbranch_execz .LBB0_407
	v_mov_b32_e32 v3, v216
	v_mul_f32_e32 v3, v11, v3
	v_mul_f32_e32 v3, v2, v3

.LBB0_408:
	s_or_b64 exec, exec, s[38:39]
	v_mov_b32_e32 v2, 0
	ds_write_b32 v147, v3 offset:4624
	s_and_saveexec_b64 s[38:39], s[58:59]
	s_cbranch_execz .LBB0_410
	v_mov_b32_e32 v2, v217
	v_sub_f32_e32 v2, v2, v59
	v_mul_f32_e32 v2, 0x3fb8aa3b, v2
	v_exp_f32_e32 v2, v2

.LBB0_413:
	v_readlane_b32 s40, v254, 59
	v_mov_b32_e32 v3, 0
	v_readlane_b32 s41, v254, 60
	s_and_saveexec_b64 s[44:45], s[40:41]
	s_cbranch_execz .LBB0_415
	v_mov_b32_e32 v3, v218
	v_mul_f32_e32 v3, v12, v3
	v_mul_f32_e32 v3, v2, v3

.LBB0_416:
	s_or_b64 exec, exec, s[38:39]
	v_mov_b32_e32 v2, 0
	ds_write_b32 v147, v3 offset:4896
	s_and_saveexec_b64 s[38:39], s[62:63]
	s_cbranch_execz .LBB0_418
	v_mov_b32_e32 v2, v219
	v_sub_f32_e32 v2, v2, v59
	v_mul_f32_e32 v2, 0x3fb8aa3b, v2
	v_exp_f32_e32 v2, v2

.LBB0_421:
	v_readlane_b32 s40, v254, 61
	v_mov_b32_e32 v3, 0
	v_readlane_b32 s41, v254, 62
	s_and_saveexec_b64 s[44:45], s[40:41]
	s_cbranch_execz .LBB0_423
	v_mov_b32_e32 v3, v220
	v_mul_f32_e32 v3, v13, v3
	v_mul_f32_e32 v3, v2, v3

.LBB0_424:
	s_or_b64 exec, exec, s[38:39]
	v_mov_b32_e32 v2, 0
	ds_write_b32 v147, v3 offset:5168
	s_and_saveexec_b64 s[38:39], s[66:67]
	s_cbranch_execz .LBB0_426
	v_mov_b32_e32 v2, v221
	v_sub_f32_e32 v2, v2, v59
	v_mul_f32_e32 v2, 0x3fb8aa3b, v2
	v_exp_f32_e32 v2, v2

.LBB0_429:
	v_readlane_b32 s40, v254, 63
	v_mov_b32_e32 v3, 0
	v_readlane_b32 s41, v255, 0
	s_and_saveexec_b64 s[44:45], s[40:41]
	s_cbranch_execz .LBB0_431
	v_mov_b32_e32 v3, v222
	v_mul_f32_e32 v3, v14, v3
	v_mul_f32_e32 v3, v2, v3

.LBB0_432:
	s_or_b64 exec, exec, s[38:39]
	v_mov_b32_e32 v2, 0
	ds_write_b32 v147, v3 offset:6528
	s_and_saveexec_b64 s[38:39], s[20:21]
	s_cbranch_execz .LBB0_434
	v_mov_b32_e32 v2, v223
	v_sub_f32_e32 v2, v2, v59
	v_mul_f32_e32 v2, 0x3fb8aa3b, v2
	v_exp_f32_e32 v2, v2

.LBB0_437:
	v_readlane_b32 s40, v255, 1
	v_mov_b32_e32 v3, 0
	v_readlane_b32 s41, v255, 2
	s_and_saveexec_b64 s[44:45], s[40:41]
	s_cbranch_execz .LBB0_439
	v_mov_b32_e32 v3, v224
	v_mul_f32_e32 v3, v15, v3
	v_mul_f32_e32 v3, v2, v3

.LBB0_440:
	s_or_b64 exec, exec, s[38:39]
	v_mov_b32_e32 v2, 0
	ds_write_b32 v147, v3 offset:6800
	s_and_saveexec_b64 s[38:39], s[26:27]
	s_cbranch_execz .LBB0_442
	v_mov_b32_e32 v2, v225
	v_sub_f32_e32 v2, v2, v59
	v_mul_f32_e32 v2, 0x3fb8aa3b, v2
	v_exp_f32_e32 v2, v2

.LBB0_445:
	v_readlane_b32 s40, v255, 3
	v_mov_b32_e32 v3, 0
	v_readlane_b32 s41, v255, 4
	s_and_saveexec_b64 s[44:45], s[40:41]
	s_cbranch_execz .LBB0_447
	v_mov_b32_e32 v3, v226
	v_mul_f32_e32 v3, v16, v3
	v_mul_f32_e32 v3, v2, v3

.LBB0_448:
	s_or_b64 exec, exec, s[38:39]
	v_mov_b32_e32 v2, 0
	ds_write_b32 v147, v3 offset:7072
	s_and_saveexec_b64 s[38:39], s[0:1]
	s_cbranch_execz .LBB0_450
	v_mov_b32_e32 v2, v227
	v_sub_f32_e32 v2, v2, v59
	v_mul_f32_e32 v2, 0x3fb8aa3b, v2
	v_exp_f32_e32 v2, v2

.LBB0_453:
	v_readlane_b32 s40, v255, 5
	v_mov_b32_e32 v3, 0
	v_readlane_b32 s41, v255, 6
	s_and_saveexec_b64 s[44:45], s[40:41]
	s_cbranch_execz .LBB0_455
	v_mov_b32_e32 v3, v228
	v_mul_f32_e32 v3, v17, v3
	v_mul_f32_e32 v3, v2, v3
